# v32: v31 + sb_attn block counter decrement on the SALU (s_sub_u32 + s_cselect instead of v_sub_co + readfirstlane) + LN1 no-route prologue: drop the vmcnt(0) behind the gain/bias loads
# speedup vs baseline: 1.0017x; 1.0014x over previous
; __device__ __forceinline__ void sb_attn(Frame& F) {
;     ...
;             if (kb > 0) {
;                 const bf16* Kp = PROJ + (tok0 + 32 * (kb - 1) + r32) * NPROJ + C_SK + 64 * h + 8 * hi;
; #pragma unroll
;                 for (int ds = 0; ds < 4; ++ds) kf[ds] = *(const bf16x8*)(Kp + 16 * ds);
; #pragma unroll
;                 for (int n = 0; n < 4; ++n) { const int idx = lane + 64 * n; vreg[n] = *(const u32x4*)(PROJ + (tok0 + 32 * (kb - 1) + (idx >> 3)) * NPROJ + C_SV + 64 * h + 8 * (idx & 7)); }
.LBB0_316:
	s_sub_u32 s24, s24, 1
	s_cselect_b64 s[90:91], -1, 0
	s_and_b64 vcc, exec, s[90:91]
	s_cbranch_vccnz .LBB0_318
	s_add_u32 s100, s100, 0xfffc8000
	s_addc_u32 s101, s101, -1
	v_mov_b32_e32 v215, v67
	global_load_dwordx4 v[168:171], v239, s[100:101] offset:1056
	global_load_dwordx4 v[172:175], v239, s[100:101] offset:1088
	global_load_dwordx4 v[164:167], v239, s[100:101] offset:1024
	global_load_dwordx4 v[176:179], v239, s[100:101] offset:1120
	global_load_dwordx4 v[180:183], v240, s[100:101] offset:2048
	global_load_dwordx4 v[184:187], v241, s[100:101] offset:2048
	global_load_dwordx4 v[188:191], v242, s[100:101] offset:2048
	global_load_dwordx4 v[192:195], v243, s[100:101] offset:2048

; __device__ __forceinline__ float wave_sum(float v) {
; #pragma unroll
;     for (int o = 1; o < 64; o <<= 1) v += __shfl_xor(v, o);
; template <int MODE, bool ROUTE, int H8> ...
;     ...
;     f32x4 g4[4], b4[4];
; #pragma unroll
;     for (int jj = 0; jj < 4; ++jj) { g4[jj] = *(const f32x4*)(lng + 4 * F.lane + 256 * jj); b4[jj] = *(const f32x4*)(lnb + 4 * F.lane + 256 * jj); }
;     for (int blk = gw; blk < M / 32; blk += NGW) {
;         const int row0 = blk * 32, b = row0 / SEQ;
;         f32x4 gt[4], nsh[4], nsc[4];
; #pragma unroll
;         for (int jj = 0; jj < 4; ++jj) { gt[jj] = *(const f32x4*)(gate_mod + (size_t)b * 3072 + 2048 + 4 * F.lane + 256 * jj);
;             if (next_mod) { nsh[jj] = *(const f32x4*)(next_mod + (size_t)b * 3072 + 4 * F.lane + 256 * jj); nsc[jj] = *(const f32x4*)(next_mod + (size_t)b * 3072 + 1024 + 4 * F.lane + 256 * jj); }
;             else { nsh[jj] = (f32x4){0.f, 0.f, 0.f, 0.f}; nsc[jj] = nsh[jj]; } }
;         f32x4 xq[4]; u32x2 xhq[4], yq0[4], yq1[4];
;     ...
;         unsigned wq0 = 0u, wq1 = 0u;
;         LN_LOAD(0);
.LBB0_829:
	s_and_b64 vcc, exec, s[12:13]
	s_mov_b32 s64, 0x10000
	s_mov_b64 s[74:75], 0x30080
	s_mov_b32 s86, s76
	s_cbranch_vccz .LBB0_870
	v_mov_b32_e32 v2, v0
	v_readlane_b32 s40, v255, 2
	v_readfirstlane_b32 s2, v2
	s_ashr_i32 s2, s2, 6
	s_mov_b64 s[6:7], 0
	v_readlane_b32 s69, v253, 36
	s_mov_b32 s70, s66
	v_readlane_b32 s44, v255, 6
	v_readlane_b32 s45, v255, 7
	s_add_u32 s72, s44, s6
	s_addc_u32 s73, s45, s7
	s_lshl_b32 s3, s70, 3
	s_add_i32 s6, s3, s2
	s_cmpk_gt_i32 s6, 0x7ff
	v_readlane_b32 s41, v255, 3
	v_readlane_b32 s42, v255, 4
	v_readlane_b32 s43, v255, 5
	v_readlane_b32 s46, v255, 8
	v_readlane_b32 s47, v255, 9
	s_cbranch_scc1 .LBB0_870
	v_lshlrev_b32_e32 v2, 2, v2
	v_and_b32_e32 v66, 0xfc, v2
	v_lshlrev_b32_e32 v10, 2, v66
	global_load_dwordx4 v[2:5], v10, s[8:9]
	global_load_dwordx4 v[6:9], v10, s[8:9] offset:1024
	global_load_dwordx4 v[16:19], v10, s[10:11]
	global_load_dwordx4 v[20:23], v10, s[10:11] offset:1024
	global_load_dwordx4 v[24:27], v10, s[8:9] offset:2048
	global_load_dwordx4 v[28:31], v10, s[8:9] offset:3072
	global_load_dwordx4 v[32:35], v10, s[10:11] offset:2048
	s_waitcnt lgkmcnt(0)
	global_load_dwordx4 v[36:39], v10, s[10:11] offset:3072
	v_and_b32_e32 v12, 64, v223
	v_add_u32_e32 v12, 64, v12
	v_xor_b32_e32 v13, 1, v223
	v_cmp_lt_i32_e32 vcc, v13, v12
	v_readlane_b32 s40, v253, 2
	v_mov_b32_e32 v11, v67
	v_cndmask_b32_e32 v13, v223, v13, vcc
	v_lshlrev_b32_e32 v158, 2, v13
	v_xor_b32_e32 v13, 2, v223
	v_cmp_lt_i32_e32 vcc, v13, v12
	v_readlane_b32 s41, v253, 3
	s_mov_b64 s[8:9], 0x38000000
	v_cndmask_b32_e32 v13, v223, v13, vcc
	v_lshlrev_b32_e32 v159, 2, v13
	v_xor_b32_e32 v13, 4, v223
	v_cmp_lt_i32_e32 vcc, v13, v12
	v_lshl_add_u64 v[64:65], s[40:41], 0, v[10:11]
	v_lshlrev_b32_e32 v10, 1, v66
	v_cndmask_b32_e32 v13, v223, v13, vcc
	v_lshlrev_b32_e32 v160, 2, v13
	v_xor_b32_e32 v13, 8, v223
	v_cmp_lt_i32_e32 vcc, v13, v12
	s_lshl_b32 s3, s70, 8
	s_lshl_b32 s2, s2, 5
	v_cndmask_b32_e32 v13, v223, v13, vcc
	v_lshlrev_b32_e32 v161, 2, v13
	v_xor_b32_e32 v13, 16, v223
	v_cmp_lt_i32_e32 vcc, v13, v12
	v_mov_b32_e32 v88, 0
	s_lshl_b32 s7, s69, 3
	v_cndmask_b32_e32 v13, v223, v13, vcc
	v_lshlrev_b32_e32 v162, 2, v13
	v_xor_b32_e32 v13, 32, v223
	v_cmp_lt_i32_e32 vcc, v13, v12
	s_add_i32 s12, s3, s2
	s_lshl_b32 s13, s69, 8
	v_cndmask_b32_e32 v12, v223, v13, vcc
	v_lshlrev_b32_e32 v163, 2, v12
	v_lshl_add_u64 v[12:13], s[72:73], 0, v[10:11]
	v_lshl_add_u64 v[104:105], v[12:13], 0, s[8:9]
	v_readlane_b32 s8, v255, 10
	v_readlane_b32 s9, v255, 11
	v_mov_b32_e32 v89, v88
	v_mov_b32_e32 v90, v88
	v_lshl_add_u64 v[106:107], s[8:9], 0, v[10:11]
	v_lshl_add_u64 v[10:11], s[72:73], 0, v[66:67]
	s_mov_b64 s[8:9], 0xb900000
	v_lshl_add_u64 v[108:109], v[10:11], 0, s[8:9]
	v_lshlrev_b32_e32 v66, 2, v66
	v_mov_b32_e32 v91, v88
	v_mov_b32_e32 v84, v88
	v_mov_b32_e32 v85, v88
	v_mov_b32_e32 v86, v88
	v_mov_b32_e32 v87, v88
	v_mov_b32_e32 v80, v88
	v_mov_b32_e32 v81, v88
	v_mov_b32_e32 v82, v88
	v_mov_b32_e32 v83, v88
	v_mov_b32_e32 v76, v88
	v_mov_b32_e32 v77, v88
	v_mov_b32_e32 v78, v88
	v_mov_b32_e32 v79, v88
	v_readlane_b32 s42, v253, 4
	v_readlane_b32 s43, v253, 5
	v_readlane_b32 s44, v253, 6
	v_readlane_b32 s45, v253, 7
	v_readlane_b32 s46, v253, 8
	v_readlane_b32 s47, v253, 9
	v_readlane_b32 s48, v253, 10
	v_readlane_b32 s49, v253, 11
	v_readlane_b32 s50, v253, 12
	v_readlane_b32 s51, v253, 13
	v_readlane_b32 s52, v253, 14
	v_readlane_b32 s53, v253, 15
	v_readlane_b32 s54, v253, 16
	v_readlane_b32 s55, v253, 17
	s_branch .LBB0_833
